# post_rows: rope partner shuffles of q_rope and k_rope batched (one LDS round trip per block instead of eight)
# speedup vs baseline: 1.0071x; 1.0034x over previous
.LBB0_253:
	s_or_b64 exec, exec, s[72:73]
	s_waitcnt vmcnt(7)
	v_and_b32_e32 v143, 0xffff0000, v120
	v_lshlrev_b32_e32 v141, 16, v120
	v_mul_f32_e32 v156, v143, v143
	v_lshlrev_b32_e32 v145, 16, v121
	v_fmac_f32_e32 v156, v141, v141
	v_and_b32_e32 v155, 0xffff0000, v121
	v_fmac_f32_e32 v156, v145, v145
	v_lshlrev_b32_e32 v158, 16, v122
	v_fmac_f32_e32 v156, v155, v155
	v_and_b32_e32 v159, 0xffff0000, v122
	v_fmac_f32_e32 v156, v158, v158
	v_lshlrev_b32_e32 v160, 16, v123
	v_fmac_f32_e32 v156, v159, v159
	v_and_b32_e32 v161, 0xffff0000, v123
	v_fmac_f32_e32 v156, v160, v160
	v_and_b32_e32 v120, 0xffff0000, v116
	v_lshlrev_b32_e32 v121, 16, v116
	v_fmac_f32_e32 v156, v161, v161
	v_pk_mul_f32 v[122:123], v[120:121], v[120:121]
	v_lshl_or_b32 v92, v95, 3, v148
	v_add_f32_e32 v116, v123, v156
	v_add_f32_e32 v156, v122, v116
	v_and_b32_e32 v116, 0xffff0000, v117
	v_lshlrev_b32_e32 v117, 16, v117
	v_pk_mul_f32 v[122:123], v[116:117], v[116:117]
	v_ashrrev_i32_e32 v93, 31, v92
	v_add_f32_e32 v123, v123, v156
	v_add_f32_e32 v162, v122, v123
	v_and_b32_e32 v122, 0xffff0000, v118
	v_lshlrev_b32_e32 v123, 16, v118
	v_pk_mul_f32 v[156:157], v[122:123], v[122:123]
	v_lshlrev_b64 v[96:97], 7, v[124:125]
	v_add_f32_e32 v118, v157, v162
	v_add_f32_e32 v162, v156, v118
	v_and_b32_e32 v118, 0xffff0000, v119
	v_lshlrev_b32_e32 v119, 16, v119
	v_pk_mul_f32 v[156:157], v[118:119], v[118:119]
	v_lshlrev_b64 v[92:93], 13, v[92:93]
	v_add_f32_e32 v157, v157, v162
	v_add_f32_e32 v156, v156, v157
	ds_bpermute_b32 v157, v149, v156
	v_ashrrev_i32_e32 v95, 31, v94
	v_lshl_add_u64 v[98:99], v[128:129], 0, v[96:97]
	v_lshl_add_u64 v[108:109], v[130:131], 0, v[96:97]
	v_lshl_add_u64 v[146:147], v[92:93], 0, v[94:95]
	global_load_dwordx4 v[92:95], v[98:99], off offset:16
	global_load_dwordx4 v[104:107], v[98:99], off
	s_nop 0
	global_load_dwordx4 v[96:99], v[108:109], off offset:16
	s_nop 0
	global_load_dwordx4 v[108:111], v[108:109], off
	s_waitcnt lgkmcnt(0)
	v_add_f32_e32 v156, v156, v157
	ds_bpermute_b32 v157, v150, v156
	s_movk_i32 s1, 0x180
	s_waitcnt lgkmcnt(0)
	v_add_f32_e32 v156, v156, v157
	ds_bpermute_b32 v157, v151, v156
	s_waitcnt lgkmcnt(0)
	v_add_f32_e32 v156, v156, v157
	v_fmamk_f32 v156, v156, 0x3c000000, v189
	v_cmp_gt_f32_e32 vcc, s33, v156
	v_mul_f32_e32 v157, 0x4b800000, v156
	s_nop 0
	v_cndmask_b32_e32 v156, v156, v157, vcc
	v_rsq_f32_e32 v156, v156
	s_nop 0
	v_mul_f32_e32 v157, 0x45800000, v156
	v_cndmask_b32_e32 v156, v156, v157, vcc
	v_mul_f32_e32 v156, 0x3dd53b94, v156
	v_mul_f32_e32 v141, v156, v141
	v_mul_f32_e32 v157, v0, v141
	v_mul_f32_e32 v141, v156, v143
	v_mul_f32_e32 v143, v1, v141
	v_mul_f32_e32 v141, v156, v145
	v_mul_f32_e32 v116, v156, v116
	v_mul_f32_e32 v145, v2, v141
	v_mul_f32_e32 v141, v156, v155
	v_mul_f32_e32 v165, v11, v116
	v_mul_f32_e32 v116, v156, v123
	v_mul_f32_e32 v155, v3, v141
	v_mul_f32_e32 v141, v156, v158
	v_mul_f32_e32 v166, v12, v116
	v_mul_f32_e32 v116, v156, v122
	v_mul_f32_e32 v158, v4, v141
	v_mul_f32_e32 v141, v156, v159
	v_mul_f32_e32 v167, v13, v116
	v_mul_f32_e32 v116, v156, v119
	v_mul_f32_e32 v159, v5, v141
	v_mul_f32_e32 v141, v156, v160
	v_mul_f32_e32 v117, v156, v117
	v_mul_f32_e32 v168, v14, v116
	v_mul_f32_e32 v116, v156, v118
	v_mul_f32_e32 v160, v6, v141
	v_mul_f32_e32 v141, v156, v161
	v_mul_f32_e32 v121, v156, v121
	v_mul_f32_e32 v120, v156, v120
	v_mul_f32_e32 v164, v10, v117
	v_mul_f32_e32 v156, v15, v116
	v_mov_b64_e32 v[116:117], s[70:71]
	v_mad_u64_u32 v[116:117], s[2:3], v146, s1, v[116:117]
	v_mul_f32_e32 v161, v7, v141
	v_mad_i32_i24 v117, v147, s1, v117
	v_mov_b32_e32 v141, v177
	v_lshl_add_u64 v[122:123], v[116:117], 0, v[140:141]
	v_cvt_pk_bf16_f32 v118, v157, v143
	v_cvt_pk_bf16_f32 v119, v145, v155
	v_mul_f32_e32 v162, v8, v121
	v_mul_f32_e32 v163, v9, v120
	v_cvt_pk_bf16_f32 v120, v158, v159
	v_cvt_pk_bf16_f32 v121, v160, v161
	global_store_dwordx4 v[122:123], v[118:121], off
	s_waitcnt vmcnt(11)
	v_lshlrev_b32_e32 v157, 16, v114
	v_mov_b32_e32 v143, v177
	v_cvt_pk_bf16_f32 v118, v162, v163
	v_cvt_pk_bf16_f32 v119, v164, v165
	v_cvt_pk_bf16_f32 v120, v166, v167
	v_cvt_pk_bf16_f32 v121, v168, v156
	global_store_dwordx4 v[122:123], v[118:121], off offset:16
	v_and_b32_e32 v156, 0xffff0000, v114
	v_pk_mul_f32 v[158:159], v[156:157], v[156:157]
	v_lshlrev_b32_e32 v118, 16, v112
	v_and_b32_e32 v119, 0xffff0000, v112
	v_pk_mul_f32 v[120:121], v[118:119], v[118:119]
	v_and_b32_e32 v112, 0xffff0000, v113
	v_lshlrev_b32_e32 v113, 16, v113
	v_pk_mul_f32 v[122:123], v[112:113], v[112:113]
	v_add_f32_e32 v120, v120, v121
	v_add_f32_e32 v120, v123, v120
	v_add_f32_e32 v120, v122, v120
	v_and_b32_e32 v114, 0xffff0000, v115
	v_lshlrev_b32_e32 v115, 16, v115
	v_add_f32_e32 v120, v159, v120
	v_pk_mul_f32 v[160:161], v[114:115], v[114:115]
	v_add_f32_e32 v120, v158, v120
	v_add_f32_e32 v120, v161, v120
	v_add_f32_e32 v120, v160, v120
	ds_bpermute_b32 v121, v149, v120
	v_lshl_add_u64 v[116:117], v[116:117], 0, v[142:143]
	v_mov_b32_e32 v145, v177
	s_waitcnt lgkmcnt(0)
	v_add_f32_e32 v120, v120, v121
	ds_bpermute_b32 v121, v150, v120
	s_waitcnt lgkmcnt(0)
	v_add_f32_e32 v120, v120, v121
	ds_bpermute_b32 v121, v151, v120
	s_waitcnt lgkmcnt(0)
	v_add_f32_e32 v120, v120, v121
	v_fmamk_f32 v120, v120, 0x3c800000, v189
	v_cmp_gt_f32_e32 vcc, s33, v120
	v_mul_f32_e32 v121, 0x4b800000, v120
	s_nop 0
	v_cndmask_b32_e32 v120, v120, v121, vcc
	v_rsq_f32_e32 v120, v120
	s_nop 0
	v_mul_f32_e32 v121, 0x45800000, v120
	v_cndmask_b32_e32 v120, v120, v121, vcc
	v_mul_f32_e32 v120, 0x3dd53b94, v120
	v_mul_f32_e32 v118, v120, v118
	v_mul_f32_e32 v118, v48, v118
	v_mul_f32_e32 v119, v120, v119
	v_mul_f32_e32 v119, v49, v119
	v_mul_f32_e32 v113, v120, v113
	v_mul_f32_e32 v113, v50, v113
	v_mul_f32_e32 v112, v120, v112
	v_mul_f32_e32 v112, v51, v112
	v_mul_f32_e32 v157, v120, v157
	v_mul_f32_e32 v157, v52, v157
	v_mul_f32_e32 v156, v120, v156
	v_mul_f32_e32 v156, v53, v156
	v_mul_f32_e32 v115, v120, v115
	v_mul_f32_e32 v115, v54, v115
	v_mul_f32_e32 v114, v120, v114
	v_mul_f32_e32 v114, v55, v114
	ds_bpermute_b32 v200, v149, v118
	ds_bpermute_b32 v201, v149, v119
	ds_bpermute_b32 v202, v149, v113
	ds_bpermute_b32 v203, v149, v112
	ds_bpermute_b32 v204, v149, v157
	ds_bpermute_b32 v205, v149, v156
	ds_bpermute_b32 v206, v149, v115
	ds_bpermute_b32 v207, v149, v114
	s_waitcnt vmcnt(2) lgkmcnt(0)
	v_mul_f32_e32 v200, v108, v200
	v_mul_f32_e32 v201, v109, v201
	v_mul_f32_e32 v202, v110, v202
	v_mul_f32_e32 v203, v111, v203
	v_mul_f32_e32 v204, v96, v204
	v_mul_f32_e32 v205, v97, v205
	v_mul_f32_e32 v206, v98, v206
	v_mul_f32_e32 v207, v99, v207
	v_cndmask_b32_e64 v200, v200, -v200, s[40:41]
	v_cndmask_b32_e64 v201, v201, -v201, s[40:41]
	v_cndmask_b32_e64 v202, v202, -v202, s[40:41]
	v_cndmask_b32_e64 v203, v203, -v203, s[40:41]
	v_cndmask_b32_e64 v204, v204, -v204, s[40:41]
	v_cndmask_b32_e64 v205, v205, -v205, s[40:41]
	v_cndmask_b32_e64 v206, v206, -v206, s[40:41]
	v_cndmask_b32_e64 v207, v207, -v207, s[40:41]
	v_fmac_f32_e32 v200, v104, v118
	v_fmac_f32_e32 v201, v105, v119
	v_fmac_f32_e32 v202, v106, v113
	v_fmac_f32_e32 v203, v107, v112
	v_fmac_f32_e32 v204, v92, v157
	v_fmac_f32_e32 v205, v93, v156
	v_fmac_f32_e32 v206, v94, v115
	v_fmac_f32_e32 v207, v95, v114
	v_mov_b32_e32 v121, v200
	v_mov_b32_e32 v119, v201
	v_mov_b32_e32 v118, v202
	v_mov_b32_e32 v113, v203
	v_mov_b32_e32 v122, v204
	v_mov_b32_e32 v123, v205
	v_mov_b32_e32 v115, v206
	v_mov_b32_e32 v120, v207
	v_cvt_pk_bf16_f32 v112, v121, v119
	v_cvt_pk_bf16_f32 v113, v118, v113
	v_cvt_pk_bf16_f32 v114, v122, v123
	v_cvt_pk_bf16_f32 v115, v115, v120
	global_store_dwordx4 v[116:117], v[112:115], off offset:256
	v_and_b32_e32 v118, 0xffff0000, v102
	v_lshlrev_b32_e32 v119, 16, v102
	v_lshlrev_b32_e32 v112, 16, v100
	v_and_b32_e32 v113, 0xffff0000, v100
	v_pk_mul_f32 v[114:115], v[112:113], v[112:113]
	v_and_b32_e32 v100, 0xffff0000, v101
	v_lshlrev_b32_e32 v101, 16, v101
	v_pk_mul_f32 v[116:117], v[100:101], v[100:101]
	v_add_f32_e32 v114, v114, v115
	v_add_f32_e32 v114, v117, v114
	v_pk_mul_f32 v[120:121], v[118:119], v[118:119]
	v_add_f32_e32 v114, v116, v114
	v_and_b32_e32 v102, 0xffff0000, v103
	v_lshlrev_b32_e32 v103, 16, v103
	v_add_f32_e32 v114, v121, v114
	v_pk_mul_f32 v[122:123], v[102:103], v[102:103]
	v_add_f32_e32 v114, v120, v114
	v_add_f32_e32 v114, v123, v114
	v_add_f32_e32 v114, v122, v114
	ds_bpermute_b32 v115, v149, v114
	s_waitcnt lgkmcnt(0)
	v_add_f32_e32 v114, v114, v115
	ds_bpermute_b32 v115, v150, v114
	s_waitcnt lgkmcnt(0)
	v_add_f32_e32 v114, v114, v115
	ds_bpermute_b32 v115, v151, v114
	s_waitcnt lgkmcnt(0)
	v_add_f32_e32 v114, v114, v115
	v_fmamk_f32 v114, v114, 0x3c800000, v189
	v_cmp_gt_f32_e32 vcc, s33, v114
	v_mul_f32_e32 v115, 0x4b800000, v114
	s_nop 0
	v_cndmask_b32_e32 v114, v114, v115, vcc
	v_rsq_f32_e32 v114, v114
	s_nop 0
	v_mul_f32_e32 v115, 0x45800000, v114
	v_cndmask_b32_e32 v114, v114, v115, vcc
	v_mul_f32_e32 v112, v114, v112
	v_mul_f32_e32 v112, v40, v112
	v_mul_f32_e32 v113, v114, v113
	v_mul_f32_e32 v113, v41, v113
	v_mul_f32_e32 v101, v114, v101
	v_mul_f32_e32 v101, v42, v101
	v_mul_f32_e32 v100, v114, v100
	v_mul_f32_e32 v100, v43, v100
	v_mul_f32_e32 v119, v114, v119
	v_mul_f32_e32 v119, v44, v119
	v_mul_f32_e32 v118, v114, v118
	v_mul_f32_e32 v118, v45, v118
	v_mul_f32_e32 v103, v114, v103
	v_mul_f32_e32 v103, v46, v103
	v_mul_f32_e32 v102, v114, v102
	v_mul_f32_e32 v102, v47, v102
	ds_bpermute_b32 v200, v149, v112
	ds_bpermute_b32 v201, v149, v113
	ds_bpermute_b32 v202, v149, v101
	ds_bpermute_b32 v203, v149, v100
	ds_bpermute_b32 v204, v149, v119
	ds_bpermute_b32 v205, v149, v118
	ds_bpermute_b32 v206, v149, v103
	ds_bpermute_b32 v207, v149, v102
	s_waitcnt lgkmcnt(0)
	v_mul_f32_e32 v200, v108, v200
	v_mul_f32_e32 v201, v109, v201
	v_mul_f32_e32 v202, v110, v202
	v_mul_f32_e32 v203, v111, v203
	v_mul_f32_e32 v204, v96, v204
	v_mul_f32_e32 v205, v97, v205
	v_mul_f32_e32 v206, v98, v206
	v_mul_f32_e32 v207, v99, v207
	v_cndmask_b32_e64 v200, v200, -v200, s[40:41]
	v_cndmask_b32_e64 v201, v201, -v201, s[40:41]
	v_cndmask_b32_e64 v202, v202, -v202, s[40:41]
	v_cndmask_b32_e64 v203, v203, -v203, s[40:41]
	v_cndmask_b32_e64 v204, v204, -v204, s[40:41]
	v_cndmask_b32_e64 v205, v205, -v205, s[40:41]
	v_cndmask_b32_e64 v206, v206, -v206, s[40:41]
	v_cndmask_b32_e64 v207, v207, -v207, s[40:41]
	v_fmac_f32_e32 v200, v104, v112
	v_fmac_f32_e32 v201, v105, v113
	v_fmac_f32_e32 v202, v106, v101
	v_fmac_f32_e32 v203, v107, v100
	v_fmac_f32_e32 v204, v92, v119
	v_fmac_f32_e32 v205, v93, v118
	v_fmac_f32_e32 v206, v94, v103
	v_fmac_f32_e32 v207, v95, v102
	v_mov_b32_e32 v108, v200
	v_mov_b32_e32 v109, v201
	v_mov_b32_e32 v104, v202
	v_mov_b32_e32 v101, v203
	v_mov_b32_e32 v96, v204
	v_mov_b32_e32 v97, v205
	v_mov_b32_e32 v98, v206
	v_mov_b32_e32 v99, v207
	v_lshlrev_b32_e32 v100, 16, v85
	v_and_b32_e32 v103, 0xffff0000, v85
	v_and_b32_e32 v85, 0xffff0000, v86
	v_and_b32_e32 v102, 0xffff0000, v81
	v_cvt_pk_bf16_f32 v92, v108, v109
	v_cvt_pk_bf16_f32 v93, v104, v101
	v_cvt_pk_bf16_f32 v94, v96, v97
	v_mov_b64_e32 v[96:97], s[68:69]
	v_mad_u64_u32 v[96:97], s[2:3], v146, s1, v[96:97]
	v_mad_i32_i24 v97, v147, s1, v97
	v_lshl_add_u64 v[96:97], v[96:97], 0, v[142:143]
	s_mov_b32 s1, 0x2b000000
	v_add_co_u32_e32 v96, vcc, s1, v96
	v_cvt_pk_bf16_f32 v95, v98, v99
	v_lshlrev_b32_e32 v101, 16, v81
	s_nop 0
	v_addc_co_u32_e32 v97, vcc, 0, v97, vcc
	global_store_dwordx4 v[96:97], v[92:95], off offset:256
	v_lshlrev_b32_e32 v96, 16, v89
	v_and_b32_e32 v97, 0xffff0000, v89
	v_and_b32_e32 v95, 0xffff0000, v88
	v_lshlrev_b32_e32 v94, 16, v88
	v_mul_f32_e32 v98, v95, v95
	v_fmac_f32_e32 v98, v94, v94
	v_fmac_f32_e32 v98, v96, v96
	v_and_b32_e32 v88, 0xffff0000, v90
	v_lshlrev_b32_e32 v89, 16, v90
	v_fmac_f32_e32 v98, v97, v97
	v_pk_mul_f32 v[92:93], v[88:89], v[88:89]
	v_and_b32_e32 v81, 0xffff0000, v82
	v_add_f32_e32 v90, v93, v98
	v_add_f32_e32 v98, v92, v90
	v_and_b32_e32 v90, 0xffff0000, v91
	v_lshlrev_b32_e32 v91, 16, v91
	v_pk_mul_f32 v[92:93], v[90:91], v[90:91]
	v_and_b32_e32 v99, 0xffff0000, v84
	v_add_f32_e32 v93, v93, v98
	v_add_f32_e32 v92, v92, v93
	ds_bpermute_b32 v93, v152, v92
	s_waitcnt lgkmcnt(0)
	v_add_f32_e32 v92, v92, v93
	ds_bpermute_b32 v93, v153, v92
	s_waitcnt lgkmcnt(0)
	v_add_f32_e32 v92, v92, v93
	ds_bpermute_b32 v93, v154, v92
	s_waitcnt lgkmcnt(0)
	v_add_f32_e32 v92, v92, v93
	ds_bpermute_b32 v93, v149, v92
	s_waitcnt lgkmcnt(0)
	v_add_f32_e32 v92, v92, v93
	ds_bpermute_b32 v93, v150, v92
	s_waitcnt lgkmcnt(0)
	v_add_f32_e32 v92, v92, v93
	ds_bpermute_b32 v93, v151, v92
	s_waitcnt lgkmcnt(0)
	v_add_f32_e32 v92, v92, v93
	v_fmamk_f32 v92, v92, 0x3b000000, v189
	v_cmp_gt_f32_e32 vcc, s33, v92
	v_mul_f32_e32 v93, 0x4b800000, v92
	s_nop 0
	v_cndmask_b32_e32 v92, v92, v93, vcc
	v_rsq_f32_e32 v92, v92
	s_nop 0
	v_mul_f32_e32 v93, 0x45800000, v92
	v_cndmask_b32_e32 v92, v92, v93, vcc
	v_mul_f32_e32 v93, v92, v94
	v_mul_f32_e32 v94, v92, v95
	v_mul_f32_e32 v95, v92, v96
	v_mul_f32_e32 v96, v92, v97
	v_mul_f32_e32 v97, v92, v89
	v_mul_f32_e32 v98, v92, v88
	v_mul_f32_e32 v91, v92, v91
	v_mul_f32_e32 v92, v92, v90
	v_cvt_pk_bf16_f32 v88, v93, v94
	v_cvt_pk_bf16_f32 v89, v95, v96
	v_cvt_pk_bf16_f32 v90, v97, v98
	v_cvt_pk_bf16_f32 v91, v91, v92
	v_lshlrev_b64 v[92:93], 10, v[124:125]
	v_lshlrev_b32_e32 v96, 16, v80
	v_lshlrev_b32_e32 v97, 16, v84
	v_lshl_add_u64 v[92:93], v[126:127], 0, v[92:93]
	v_and_b32_e32 v98, 0xffff0000, v80
	v_lshlrev_b32_e32 v80, 16, v82
	v_mul_f32_e32 v82, v96, v97
	global_store_dwordx4 v[92:93], v[88:91], off
	v_and_b32_e32 v92, 0xffff0000, v57
	v_and_b32_e32 v93, 0xffff0000, v60
	v_lshlrev_b32_e32 v88, 16, v56
	v_and_b32_e32 v90, 0xffff0000, v56
	v_lshlrev_b32_e32 v91, 16, v57
	v_lshlrev_b32_e32 v89, 16, v60
	v_lshlrev_b32_e32 v94, 16, v61
	v_and_b32_e32 v95, 0xffff0000, v61
	v_lshlrev_b32_e32 v84, 16, v86
	v_lshlrev_b32_e32 v56, 16, v87
	v_lshlrev_b32_e32 v60, 16, v83
	v_and_b32_e32 v61, 0xffff0000, v83
	v_and_b32_e32 v57, 0xffff0000, v87
	v_fma_f32 v96, v16, v82, v24
	v_lshlrev_b32_e32 v83, 16, v76
	v_lshlrev_b32_e32 v82, 16, v68
	v_lshlrev_b32_e32 v87, 16, v72
	v_lshlrev_b32_e32 v86, 16, v64
	v_pk_mul_f32 v[82:83], v[82:83], v[86:87]
	v_pk_mul_f32 v[80:81], v[84:85], v[80:81]
	v_pk_mul_f32 v[82:83], v[138:139], v[82:83]
	v_pk_fma_f32 v[80:81], v[20:21], v[80:81], v[28:29]
	v_add_f32_e32 v82, v82, v96
	v_add_f32_e32 v82, v82, v83
	v_mul_f32_e32 v83, 0xbfb8aa3b, v89
	v_exp_f32_e32 v83, v83
	v_mul_f32_e32 v82, v82, v88
	v_pk_mul_f32 v[56:57], v[56:57], v[60:61]
	v_add_f32_e32 v83, 1.0, v83
	v_div_scale_f32 v86, s[2:3], v83, v83, v89
	v_rcp_f32_e32 v87, v86
	v_pk_fma_f32 v[56:57], v[22:23], v[56:57], v[30:31]
	v_fma_f32 v88, -v86, v87, 1.0
	v_fmac_f32_e32 v87, v88, v87
	v_div_scale_f32 v88, vcc, v89, v83, v89
	v_mul_f32_e32 v96, v88, v87
	v_fma_f32 v97, -v86, v96, v88
	v_fmac_f32_e32 v96, v97, v87
	v_fma_f32 v86, -v86, v96, v88
	v_div_fmas_f32 v86, v86, v87, v96
	v_div_fixup_f32 v83, v86, v83, v89
	v_and_b32_e32 v86, 0xffff0000, v68
	v_mul_f32_e32 v68, 0xbfb8aa3b, v93
	v_exp_f32_e32 v68, v68
	v_and_b32_e32 v89, 0xffff0000, v72
	v_and_b32_e32 v87, 0xffff0000, v76
	v_and_b32_e32 v88, 0xffff0000, v64
	v_add_f32_e32 v68, 1.0, v68
	v_div_scale_f32 v72, s[2:3], v68, v68, v93
	v_rcp_f32_e32 v76, v72
	v_mul_f32_e32 v82, v83, v82
	v_mul_f32_e32 v83, v98, v99
	v_pk_mul_f32 v[86:87], v[86:87], v[88:89]
	v_fma_f32 v83, v17, v83, v25
	v_pk_mul_f32 v[86:87], v[32:33], v[86:87]
	v_lshlrev_b32_e32 v89, 16, v73
	v_add_f32_e32 v64, v86, v83
	v_fma_f32 v83, -v72, v76, 1.0
	v_fmac_f32_e32 v76, v83, v76
	v_div_scale_f32 v83, vcc, v93, v68, v93
	v_mul_f32_e32 v86, v83, v76
	v_add_f32_e32 v64, v64, v87
	v_fma_f32 v87, -v72, v86, v83
	v_fmac_f32_e32 v86, v87, v76
	v_fma_f32 v72, -v72, v86, v83
	v_div_fmas_f32 v72, v72, v76, v86
	v_div_fixup_f32 v68, v72, v68, v93
	v_mul_f32_e32 v72, 0xbfb8aa3b, v94
	v_exp_f32_e32 v72, v72
	v_mul_f32_e32 v64, v64, v90
	v_lshlrev_b32_e32 v87, 16, v77
	v_lshlrev_b32_e32 v86, 16, v69
	v_lshlrev_b32_e32 v88, 16, v65
	v_mul_f32_e32 v68, v68, v64
	v_mul_f32_e32 v64, v101, v100
	v_pk_mul_f32 v[86:87], v[86:87], v[88:89]
	v_add_f32_e32 v72, 1.0, v72
	v_fma_f32 v64, v18, v64, v26
	v_pk_mul_f32 v[86:87], v[136:137], v[86:87]
	v_div_scale_f32 v76, s[2:3], v72, v72, v94
	v_add_f32_e32 v64, v86, v64
	v_rcp_f32_e32 v86, v76
	v_add_f32_e32 v64, v64, v87
	v_mul_f32_e32 v64, v64, v91
	v_and_b32_e32 v77, 0xffff0000, v77
	v_fma_f32 v87, -v76, v86, 1.0
	v_fmac_f32_e32 v86, v87, v86
	v_div_scale_f32 v87, vcc, v94, v72, v94
	v_mul_f32_e32 v88, v87, v86
	v_fma_f32 v89, -v76, v88, v87
	v_fmac_f32_e32 v88, v89, v86
	v_fma_f32 v76, -v76, v88, v87
	v_div_fmas_f32 v76, v76, v86, v88
	v_div_fixup_f32 v72, v76, v72, v94
	v_mul_f32_e32 v72, v72, v64
	v_mul_f32_e32 v64, v102, v103
	v_and_b32_e32 v76, 0xffff0000, v69
	v_and_b32_e32 v87, 0xffff0000, v73
	v_and_b32_e32 v86, 0xffff0000, v65
	v_fma_f32 v88, v19, v64, v27
	v_pk_mul_f32 v[64:65], v[76:77], v[86:87]
	v_and_b32_e32 v87, 0xffff0000, v74
	v_pk_mul_f32 v[64:65], v[34:35], v[64:65]
	v_mul_f32_e32 v83, v68, v68
	v_add_f32_e32 v64, v64, v88
	v_add_f32_e32 v64, v64, v65
	v_mul_f32_e32 v65, 0xbfb8aa3b, v95
	v_exp_f32_e32 v65, v65
	v_mul_f32_e32 v64, v64, v92
	v_fmac_f32_e32 v83, v82, v82
	v_fmac_f32_e32 v83, v72, v72
	v_add_f32_e32 v65, 1.0, v65
	v_div_scale_f32 v69, s[2:3], v65, v65, v95
	v_rcp_f32_e32 v73, v69
	s_nop 0
	v_fma_f32 v76, -v69, v73, 1.0
	v_fmac_f32_e32 v73, v76, v73
	v_div_scale_f32 v76, vcc, v95, v65, v95
	v_mul_f32_e32 v77, v76, v73
	v_fma_f32 v86, -v69, v77, v76
	v_fmac_f32_e32 v77, v86, v73
	v_fma_f32 v69, -v69, v77, v76
	v_div_fmas_f32 v69, v69, v73, v77
	v_div_fixup_f32 v65, v69, v65, v95
	v_mul_f32_e32 v69, v65, v64
	v_lshlrev_b32_e32 v65, 16, v78
	v_lshlrev_b32_e32 v64, 16, v70
	v_lshlrev_b32_e32 v77, 16, v74
	v_lshlrev_b32_e32 v76, 16, v66
	v_pk_mul_f32 v[64:65], v[64:65], v[76:77]
	v_and_b32_e32 v77, 0xffff0000, v78
	v_and_b32_e32 v76, 0xffff0000, v70
	v_and_b32_e32 v86, 0xffff0000, v66
	v_pk_mul_f32 v[76:77], v[76:77], v[86:87]
	v_and_b32_e32 v87, 0xffff0000, v58
	v_lshlrev_b32_e32 v86, 16, v58
	v_and_b32_e32 v58, 0xffff0000, v62
	v_lshlrev_b32_e32 v62, 16, v62
	v_mul_f32_e32 v66, 0xbfb8aa3b, v62
	v_exp_f32_e32 v88, v66
	v_mul_f32_e32 v66, 0xbfb8aa3b, v58
	v_exp_f32_e32 v89, v66
	v_pk_mul_f32 v[64:65], v[134:135], v[64:65]
	v_pk_mul_f32 v[76:77], v[36:37], v[76:77]
	v_mov_b32_e32 v84, v64
	v_mov_b32_e32 v85, v76
	v_pk_add_f32 v[80:81], v[84:85], v[80:81]
	v_mov_b32_e32 v76, v65
	v_pk_add_f32 v[64:65], v[80:81], v[76:77]
	v_pk_add_f32 v[76:77], v[88:89], 1.0 op_sel_hi:[1,0]
	v_pk_mul_f32 v[64:65], v[64:65], v[86:87]
	v_div_scale_f32 v66, s[2:3], v77, v77, v58
	v_rcp_f32_e32 v70, v66
	v_fmac_f32_e32 v83, v69, v69
	v_lshlrev_b32_e32 v80, 16, v67
	v_lshlrev_b32_e32 v81, 16, v75
	v_fma_f32 v73, -v66, v70, 1.0
	v_fmac_f32_e32 v70, v73, v70
	v_div_scale_f32 v73, vcc, v58, v77, v58
	v_mul_f32_e32 v74, v73, v70
	v_fma_f32 v78, -v66, v74, v73
	v_fmac_f32_e32 v74, v78, v70
	v_fma_f32 v66, -v66, v74, v73
	v_div_fmas_f32 v66, v66, v70, v74
	v_div_fixup_f32 v77, v66, v77, v58
	v_div_scale_f32 v58, s[2:3], v76, v76, v62
	v_rcp_f32_e32 v66, v58
	v_and_b32_e32 v78, 0xffff0000, v71
	v_fma_f32 v70, -v58, v66, 1.0
	v_fmac_f32_e32 v66, v70, v66
	v_div_scale_f32 v70, vcc, v62, v76, v62
	v_mul_f32_e32 v73, v70, v66
	v_fma_f32 v74, -v58, v73, v70
	v_fmac_f32_e32 v73, v74, v66
	v_fma_f32 v58, -v58, v73, v70
	v_div_fmas_f32 v58, v58, v66, v73
	v_div_fixup_f32 v76, v58, v76, v62
	v_pk_mul_f32 v[64:65], v[76:77], v[64:65]
	v_and_b32_e32 v70, 0xffff0000, v67
	v_pk_mul_f32 v[76:77], v[64:65], v[64:65]
	v_and_b32_e32 v73, 0xffff0000, v63
	v_add_f32_e32 v58, v76, v83
	v_add_f32_e32 v62, v77, v58
	v_lshlrev_b32_e32 v77, 16, v79
	v_lshlrev_b32_e32 v76, 16, v71
	v_and_b32_e32 v79, 0xffff0000, v79
	v_and_b32_e32 v71, 0xffff0000, v75
	v_lshlrev_b32_e32 v63, 16, v63
	v_pk_mul_f32 v[66:67], v[78:79], v[70:71]
	v_and_b32_e32 v71, 0xffff0000, v59
	v_lshlrev_b32_e32 v70, 16, v59
	v_mul_f32_e32 v58, 0xbfb8aa3b, v63
	v_mul_f32_e32 v59, 0xbfb8aa3b, v73
	v_exp_f32_e32 v58, v58
	v_exp_f32_e32 v59, v59
	v_pk_mul_f32 v[76:77], v[76:77], v[80:81]
	v_pk_mul_f32 v[66:67], v[38:39], v[66:67]
	v_pk_mul_f32 v[76:77], v[132:133], v[76:77]
	v_mov_b32_e32 v61, v66
	v_mov_b32_e32 v60, v76
	v_pk_add_f32 v[58:59], v[58:59], 1.0 op_sel_hi:[1,0]
	v_pk_add_f32 v[56:57], v[60:61], v[56:57]
	v_div_scale_f32 v60, s[2:3], v59, v59, v73
	v_rcp_f32_e32 v61, v60
	v_mov_b32_e32 v66, v77
	v_pk_add_f32 v[56:57], v[56:57], v[66:67]
	v_fma_f32 v66, -v60, v61, 1.0
	v_fmac_f32_e32 v61, v66, v61
	v_div_scale_f32 v66, vcc, v73, v59, v73
	v_mul_f32_e32 v67, v66, v61
	v_pk_mul_f32 v[56:57], v[56:57], v[70:71]
	v_fma_f32 v70, -v60, v67, v66
	v_fmac_f32_e32 v67, v70, v61
	v_fma_f32 v60, -v60, v67, v66
	v_div_fmas_f32 v60, v60, v61, v67
	v_div_fixup_f32 v59, v60, v59, v73
	v_div_scale_f32 v60, s[2:3], v58, v58, v63
	v_rcp_f32_e32 v61, v60
	s_nop 0
	v_fma_f32 v66, -v60, v61, 1.0
	v_fmac_f32_e32 v61, v66, v61
	v_div_scale_f32 v66, vcc, v63, v58, v63
	v_mul_f32_e32 v67, v66, v61
	v_fma_f32 v70, -v60, v67, v66
	v_fmac_f32_e32 v67, v70, v61
	v_fma_f32 v60, -v60, v67, v66
	v_div_fmas_f32 v60, v60, v61, v67
	v_div_fixup_f32 v58, v60, v58, v63
	v_pk_mul_f32 v[56:57], v[58:59], v[56:57]
	s_nop 0
	v_pk_mul_f32 v[58:59], v[56:57], v[56:57]
	s_nop 0
	v_add_f32_e32 v58, v58, v62
	v_add_f32_e32 v58, v59, v58
	ds_bpermute_b32 v59, v152, v58
	s_waitcnt lgkmcnt(0)
	v_add_f32_e32 v58, v58, v59
	ds_bpermute_b32 v59, v153, v58
	s_waitcnt lgkmcnt(0)
	v_add_f32_e32 v58, v58, v59
	ds_bpermute_b32 v59, v154, v58
	s_waitcnt lgkmcnt(0)
	v_add_f32_e32 v58, v58, v59
	ds_bpermute_b32 v59, v149, v58
	s_waitcnt lgkmcnt(0)
	v_add_f32_e32 v58, v58, v59
	ds_bpermute_b32 v59, v150, v58
	s_waitcnt lgkmcnt(0)
	v_add_f32_e32 v58, v58, v59
	ds_bpermute_b32 v59, v151, v58
	s_waitcnt lgkmcnt(0)
	v_add_f32_e32 v58, v58, v59
	v_fmamk_f32 v58, v58, 0x3b000000, v189
	v_cmp_gt_f32_e32 vcc, s33, v58
	v_mul_f32_e32 v59, 0x4b800000, v58
	s_nop 0
	v_cndmask_b32_e32 v58, v58, v59, vcc
	v_rsq_f32_e32 v58, v58
	s_nop 0
	v_mul_f32_e32 v59, 0x45800000, v58
	v_cndmask_b32_e32 v58, v58, v59, vcc
	v_mul_f32_e32 v60, v68, v58
	v_mul_f32_e32 v61, v72, v58
	v_mul_f32_e32 v59, v82, v58
	v_mul_f32_e32 v62, v69, v58
	v_mul_f32_e32 v63, v64, v58
	v_mul_f32_e32 v64, v65, v58
	v_mul_f32_e32 v65, v56, v58
	v_mul_f32_e32 v66, v57, v58
	v_cvt_pk_bf16_f32 v56, v59, v60
	v_cvt_pk_bf16_f32 v57, v61, v62
	v_lshlrev_b64 v[60:61], 12, v[124:125]
	v_lshl_add_u64 v[60:61], s[68:69], 0, v[60:61]
	v_lshl_add_u64 v[60:61], v[60:61], 0, v[144:145]
	v_add_co_u32_e32 v60, vcc, 0xd800000, v60
	v_add_u32_e32 v124, s48, v124
	s_nop 0
	v_addc_co_u32_e32 v61, vcc, 0, v61, vcc
	v_cmp_lt_i32_e32 vcc, s15, v124
	s_or_b64 s[44:45], vcc, s[44:45]
	v_cvt_pk_bf16_f32 v58, v63, v64
	v_cvt_pk_bf16_f32 v59, v65, v66
	global_store_dwordx4 v[60:61], v[56:59], off offset:3072
	s_andn2_b64 exec, exec, s[44:45]
	s_cbranch_execz .LBB0_262
